# attention y_b stores without nt hint (re-read by the merge GEMM)
# baseline (speedup 1.0000x reference)
; DI unsigned short f2bf(float f) { return (unsigned short)(cvtpk(f, f) & 0xffffu); }
; DI int crow(int r, int hi) { return (r & 3) + 8 * (r >> 2) + 4 * hi; }
; DI void attn_item(const bf16_t* __restrict__ Qw_, const bf16_t* __restrict__ Kh, const bf16_t* __restrict__ Vh, const bf16_t* Gw, bf16_t* Ow,
;                   int NT, int kt0, int qw, float sinkv, char* lds) {
;     ...
;     int lane2 = threadIdx.x & 63; asm volatile("" : "+v"(lane2));
;     const int ec = lane2 & 15, er = lane2 >> 4;
;     if (hi == 0) li_l[r32] = l_reg; asm volatile("s_waitcnt lgkmcnt(0)" ::: "memory");
;     bf16_t* OT = (bf16_t*)(lds + 67584 + wid * 8704);
; #pragma unroll
;     for (int r = 0; r < 16; ++r) { const int orow = crow(r, hi); const float rl = __builtin_amdgcn_rcpf(li_l[orow]);
; #pragma unroll
;         for (int d0 = 0; d0 < 4; ++d0) OT[orow * 136 + d0 * 32 + r32] = f2bf(o[d0][r] * rl); }
.LBB0_237:
	s_or_b64 exec, exec, s[4:5]
	s_waitcnt lgkmcnt(0)
	v_lshl_add_u32 v0, v193, 2, s54
	s_lshl_b64 s[4:5], s[14:15], 12
	ds_read_b32 v67, v0
	s_add_u32 s4, s23, s4
	s_addc_u32 s5, s30, s5
	s_lshl_b32 s14, s53, 1
	s_add_u32 s4, s4, s14
	s_addc_u32 s5, s5, 0
	s_lshr_b32 s14, s52, 6
	s_mulk_i32 s14, 0x2200
	s_waitcnt lgkmcnt(0)
	v_rcp_f32_e32 v67, v67
	s_add_i32 s14, s14, 0
	s_add_i32 s14, s14, 0x10800
	v_lshl_add_u32 v68, v188, 1, s14
	v_add_u32_e32 v69, v68, v196
	v_mul_f32_e32 v50, v50, v67
	v_mul_f32_e32 v34, v34, v67
	v_mul_f32_e32 v18, v18, v67
	v_cvt_pk_bf16_f32 v50, v50, v50
	ds_write_b16 v69, v50
	v_cvt_pk_bf16_f32 v34, v34, v34
	ds_write_b16 v69, v34 offset:64
	v_cvt_pk_bf16_f32 v18, v18, v18
	v_mul_f32_e32 v2, v2, v67
	ds_write_b16 v69, v18 offset:128
	v_cvt_pk_bf16_f32 v2, v2, v2
	ds_read_b32 v18, v0 offset:4
	ds_write_b16 v69, v2 offset:192
	v_add_u32_e32 v2, v68, v197
	s_waitcnt lgkmcnt(1)
	v_rcp_f32_e32 v18, v18
	s_nop 0
	v_mul_f32_e32 v34, v51, v18
	v_cvt_pk_bf16_f32 v34, v34, v34
	ds_write_b16 v2, v34
	v_mul_f32_e32 v34, v35, v18
	v_mul_f32_e32 v19, v19, v18
	v_mul_f32_e32 v3, v3, v18
	v_cvt_pk_bf16_f32 v34, v34, v34
	ds_write_b16 v2, v34 offset:64
	v_cvt_pk_bf16_f32 v19, v19, v19
	ds_write_b16 v2, v19 offset:128
	v_cvt_pk_bf16_f32 v3, v3, v3
	ds_read_b32 v18, v0 offset:8
	ds_write_b16 v2, v3 offset:192
	s_waitcnt lgkmcnt(1)
	v_rcp_f32_e32 v18, v18
	s_nop 0
	v_mul_f32_e32 v3, v52, v18
	v_cvt_pk_bf16_f32 v3, v3, v3
	ds_write_b16 v2, v3 offset:272
	v_mul_f32_e32 v3, v36, v18
	v_cvt_pk_bf16_f32 v3, v3, v3
	ds_write_b16 v2, v3 offset:336
	v_mul_f32_e32 v3, v20, v18
	v_cvt_pk_bf16_f32 v3, v3, v3
	ds_write_b16 v2, v3 offset:400
	v_mul_f32_e32 v3, v4, v18
	v_cvt_pk_bf16_f32 v3, v3, v3
	ds_read_b32 v4, v0 offset:12
	ds_write_b16 v2, v3 offset:464
	s_waitcnt lgkmcnt(1)
	v_rcp_f32_e32 v4, v4
	s_nop 0
	v_mul_f32_e32 v3, v53, v4
	v_cvt_pk_bf16_f32 v3, v3, v3
	ds_write_b16 v2, v3 offset:544
	v_mul_f32_e32 v3, v37, v4
	v_cvt_pk_bf16_f32 v3, v3, v3
	ds_write_b16 v2, v3 offset:608
	v_mul_f32_e32 v3, v21, v4
	v_cvt_pk_bf16_f32 v3, v3, v3
	ds_write_b16 v2, v3 offset:672
	v_mul_f32_e32 v3, v5, v4
	v_cvt_pk_bf16_f32 v3, v3, v3
	ds_read_b32 v4, v0 offset:32
	ds_write_b16 v2, v3 offset:736
	s_waitcnt lgkmcnt(1)
	v_rcp_f32_e32 v4, v4
	s_nop 0
	v_mul_f32_e32 v3, v54, v4
	v_cvt_pk_bf16_f32 v3, v3, v3
	ds_write_b16 v2, v3 offset:1904
	v_mul_f32_e32 v3, v38, v4
	v_cvt_pk_bf16_f32 v3, v3, v3
	ds_write_b16 v2, v3 offset:1968
	v_mul_f32_e32 v3, v22, v4
	v_cvt_pk_bf16_f32 v3, v3, v3
	ds_write_b16 v2, v3 offset:2032
	v_mul_f32_e32 v3, v6, v4
	v_cvt_pk_bf16_f32 v3, v3, v3
	ds_read_b32 v4, v0 offset:36
	ds_write_b16 v2, v3 offset:2096
	s_waitcnt lgkmcnt(1)
	v_rcp_f32_e32 v4, v4
	s_nop 0
	v_mul_f32_e32 v3, v55, v4
	v_cvt_pk_bf16_f32 v3, v3, v3
	ds_write_b16 v2, v3 offset:2176
	v_mul_f32_e32 v3, v39, v4
	v_cvt_pk_bf16_f32 v3, v3, v3
	ds_write_b16 v2, v3 offset:2240
	v_mul_f32_e32 v3, v23, v4
	v_cvt_pk_bf16_f32 v3, v3, v3
	ds_write_b16 v2, v3 offset:2304
	v_mul_f32_e32 v3, v7, v4
	v_cvt_pk_bf16_f32 v3, v3, v3
	ds_read_b32 v4, v0 offset:40
	ds_write_b16 v2, v3 offset:2368
	v_add_u32_e32 v3, v68, v198
	s_waitcnt lgkmcnt(1)
	v_rcp_f32_e32 v4, v4
	s_nop 0
	v_mul_f32_e32 v5, v56, v4
	v_cvt_pk_bf16_f32 v5, v5, v5
	ds_write_b16 v2, v5 offset:2448
	v_mul_f32_e32 v2, v40, v4
	v_cvt_pk_bf16_f32 v2, v2, v2
	ds_write_b16 v3, v2 offset:64
	v_mul_f32_e32 v2, v24, v4
	v_cvt_pk_bf16_f32 v2, v2, v2
	ds_write_b16 v3, v2 offset:128
	v_mul_f32_e32 v2, v8, v4
	v_cvt_pk_bf16_f32 v2, v2, v2
	ds_read_b32 v4, v0 offset:44
	ds_write_b16 v3, v2 offset:192
	s_waitcnt lgkmcnt(1)
	v_rcp_f32_e32 v4, v4
	s_nop 0
	v_mul_f32_e32 v2, v57, v4
	v_cvt_pk_bf16_f32 v2, v2, v2
	ds_write_b16 v3, v2 offset:272
	v_mul_f32_e32 v2, v41, v4
	v_cvt_pk_bf16_f32 v2, v2, v2
	ds_write_b16 v3, v2 offset:336
	v_mul_f32_e32 v2, v25, v4
	v_cvt_pk_bf16_f32 v2, v2, v2
	ds_write_b16 v3, v2 offset:400
	v_mul_f32_e32 v2, v9, v4
	v_cvt_pk_bf16_f32 v2, v2, v2
	ds_read_b32 v4, v0 offset:64
	ds_write_b16 v3, v2 offset:464
	s_waitcnt lgkmcnt(1)
	v_rcp_f32_e32 v4, v4
	s_nop 0
	v_mul_f32_e32 v2, v58, v4
	v_cvt_pk_bf16_f32 v2, v2, v2
	ds_write_b16 v3, v2 offset:1632
	v_mul_f32_e32 v2, v42, v4
	v_cvt_pk_bf16_f32 v2, v2, v2
	ds_write_b16 v3, v2 offset:1696
	v_mul_f32_e32 v2, v26, v4
	v_cvt_pk_bf16_f32 v2, v2, v2
	ds_write_b16 v3, v2 offset:1760
	v_mul_f32_e32 v2, v10, v4
	v_cvt_pk_bf16_f32 v2, v2, v2
	ds_read_b32 v4, v0 offset:68
	ds_write_b16 v3, v2 offset:1824
	s_waitcnt lgkmcnt(1)
	v_rcp_f32_e32 v4, v4
	s_nop 0
	v_mul_f32_e32 v2, v59, v4
	v_cvt_pk_bf16_f32 v2, v2, v2
	ds_write_b16 v3, v2 offset:1904
	v_mul_f32_e32 v2, v43, v4
	v_cvt_pk_bf16_f32 v2, v2, v2
	ds_write_b16 v3, v2 offset:1968
	v_mul_f32_e32 v2, v27, v4
	v_cvt_pk_bf16_f32 v2, v2, v2
	ds_write_b16 v3, v2 offset:2032
	v_mul_f32_e32 v2, v11, v4
	v_cvt_pk_bf16_f32 v2, v2, v2
	ds_read_b32 v4, v0 offset:72
	ds_write_b16 v3, v2 offset:2096
	s_waitcnt lgkmcnt(1)
	v_rcp_f32_e32 v4, v4
	s_nop 0
	v_mul_f32_e32 v2, v60, v4
	v_cvt_pk_bf16_f32 v2, v2, v2
	ds_write_b16 v3, v2 offset:2176
	v_mul_f32_e32 v2, v44, v4
	v_cvt_pk_bf16_f32 v2, v2, v2
	ds_write_b16 v3, v2 offset:2240
	v_mul_f32_e32 v2, v28, v4
	v_cvt_pk_bf16_f32 v2, v2, v2
	ds_write_b16 v3, v2 offset:2304
	v_mul_f32_e32 v2, v12, v4
	v_cvt_pk_bf16_f32 v2, v2, v2
	ds_read_b32 v4, v0 offset:76
	ds_write_b16 v3, v2 offset:2368
	s_waitcnt lgkmcnt(1)
	v_rcp_f32_e32 v4, v4
	s_nop 0
	v_mul_f32_e32 v2, v61, v4
	v_cvt_pk_bf16_f32 v2, v2, v2
	ds_write_b16 v3, v2 offset:2448
	v_mul_f32_e32 v2, v45, v4
	v_cvt_pk_bf16_f32 v2, v2, v2
	ds_write_b16 v3, v2 offset:2512
	v_mul_f32_e32 v2, v29, v4
	v_cvt_pk_bf16_f32 v2, v2, v2
	ds_write_b16 v3, v2 offset:2576
	v_mul_f32_e32 v2, v13, v4
	v_cvt_pk_bf16_f32 v2, v2, v2
	ds_read_b32 v4, v0 offset:96
	ds_write_b16 v3, v2 offset:2640
	s_waitcnt lgkmcnt(1)
; DI unsigned cvtpk(float lo, float hi) { unsigned r; asm volatile("v_cvt_pk_bf16_f32 %0, %1, %2" : "=v"(r) : "v"(lo), "v"(hi)); return r; }
; DI float bflo(unsigned w) { return __uint_as_float(w << 16); }
; DI float bfhi(unsigned w) { return __uint_as_float(w & 0xffff0000u); }
; DI float sigm(float x) { return rcpf_(1.f + ex2(-x * LOG2E)); }
; DI void attn_item(const bf16_t* __restrict__ Qw_, const bf16_t* __restrict__ Kh, const bf16_t* __restrict__ Vh, const bf16_t* Gw, bf16_t* Ow,
;                   int NT, int kt0, int qw, float sinkv, char* lds) {
;     ...
;     u32x4 gv[8];
; #pragma unroll
;     for (int k = 0; k < 8; ++k) gv[k] = __builtin_nontemporal_load((const u32x4*)(Gw + (size_t)(er + 4 * k) * 2048 + ec * 8));
;     asm volatile("s_waitcnt lgkmcnt(0)" ::: "memory");
; #pragma unroll
;     for (int k = 0; k < 8; ++k) {
;         const u32x4 ov = *(const u32x4*)(OT + (er + 4 * k) * 136 + ec * 8); u32x4 w;
; #pragma unroll
;         for (int i = 0; i < 4; ++i) { const float g0 = bflo(gv[k][i]), g1 = bfhi(gv[k][i]); w[i] = cvtpk(bflo(ov[i]) * g0 * sigm(g0), bfhi(ov[i]) * g1 * sigm(g1)); }
;         __builtin_nontemporal_store(w, (u32x4*)(Ow + (size_t)(er + 4 * k) * 2048 + ec * 8));
;     }
	v_rcp_f32_e32 v4, v4
	s_nop 0
	v_mul_f32_e32 v2, v62, v4
	v_cvt_pk_bf16_f32 v2, v2, v2
	ds_write_b16 v3, v2 offset:3808
	v_mul_f32_e32 v2, v46, v4
	v_cvt_pk_bf16_f32 v2, v2, v2
	ds_write_b16 v3, v2 offset:3872
	v_mul_f32_e32 v2, v30, v4
	v_cvt_pk_bf16_f32 v2, v2, v2
	ds_write_b16 v3, v2 offset:3936
	v_mul_f32_e32 v2, v14, v4
	v_cvt_pk_bf16_f32 v2, v2, v2
	ds_read_b32 v4, v0 offset:100
	ds_write_b16 v3, v2 offset:4000
	s_waitcnt lgkmcnt(1)
	v_rcp_f32_e32 v4, v4
	s_nop 0
	v_mul_f32_e32 v2, v63, v4
	v_cvt_pk_bf16_f32 v2, v2, v2
	ds_write_b16 v3, v2 offset:4080
	v_mul_f32_e32 v2, v47, v4
	v_cvt_pk_bf16_f32 v2, v2, v2
	ds_write_b16 v3, v2 offset:4144
	v_mul_f32_e32 v2, v31, v4
	v_cvt_pk_bf16_f32 v2, v2, v2
	ds_write_b16 v3, v2 offset:4208
	v_mul_f32_e32 v2, v15, v4
	v_cvt_pk_bf16_f32 v2, v2, v2
	ds_read_b32 v4, v0 offset:104
	ds_write_b16 v3, v2 offset:4272
	s_waitcnt lgkmcnt(1)
	v_rcp_f32_e32 v4, v4
	s_nop 0
	v_mul_f32_e32 v2, v64, v4
	v_cvt_pk_bf16_f32 v2, v2, v2
	ds_write_b16 v3, v2 offset:4352
	v_mul_f32_e32 v2, v48, v4
	v_cvt_pk_bf16_f32 v2, v2, v2
	ds_write_b16 v3, v2 offset:4416
	v_mul_f32_e32 v2, v32, v4
	v_cvt_pk_bf16_f32 v2, v2, v2
	ds_write_b16 v3, v2 offset:4480
	v_mul_f32_e32 v2, v16, v4
	v_cvt_pk_bf16_f32 v4, v2, v2
	ds_read_b32 v0, v0 offset:108
	ds_write_b16 v3, v4 offset:4544
	v_ashrrev_i32_e32 v2, 4, v66
	s_waitcnt lgkmcnt(1)
	v_rcp_f32_e32 v0, v0
	s_nop 0
	v_mul_f32_e32 v4, v65, v0
	v_cvt_pk_bf16_f32 v4, v4, v4
	ds_write_b16 v3, v4 offset:4624
	v_mul_f32_e32 v4, v49, v0
	v_cvt_pk_bf16_f32 v4, v4, v4
	ds_write_b16 v3, v4 offset:4688
	v_mul_f32_e32 v4, v33, v0
	v_mul_f32_e32 v0, v17, v0
	v_cvt_pk_bf16_f32 v4, v4, v4
	ds_write_b16 v3, v4 offset:4752
	v_cvt_pk_bf16_f32 v0, v0, v0
	ds_write_b16 v3, v0 offset:4816
	v_lshlrev_b32_e32 v0, 4, v66
	v_and_b32_e32 v0, 0xf0, v0
	v_ashrrev_i32_e32 v3, 31, v2
	v_lshl_add_u64 v[4:5], s[4:5], 0, v[0:1]
	v_lshlrev_b64 v[6:7], 12, v[2:3]
	v_lshl_add_u64 v[50:51], v[4:5], 0, v[6:7]
	global_load_dwordx4 v[38:41], v[50:51], off nt
	v_add_co_u32_e32 v52, vcc, s38, v50
	v_mul_lo_u32 v2, v2, s39
	s_nop 0
	v_addc_co_u32_e32 v53, vcc, 0, v51, vcc
	v_add_co_u32_e32 v36, vcc, s47, v50
	v_add3_u32 v0, s14, v0, v2
	s_nop 0
	v_addc_co_u32_e32 v37, vcc, 0, v51, vcc
	v_add_co_u32_e32 v34, vcc, s48, v50
	s_add_i32 s51, s51, s24
	s_nop 0
	v_addc_co_u32_e32 v35, vcc, 0, v51, vcc
	v_add_co_u32_e32 v32, vcc, s42, v50
	s_cmpk_lt_i32 s51, 0x400
	s_nop 0
	v_addc_co_u32_e32 v33, vcc, 0, v51, vcc
	v_add_co_u32_e32 v30, vcc, s49, v50
	s_waitcnt vmcnt(0)
	v_lshlrev_b32_e32 v57, 16, v38
	v_addc_co_u32_e32 v31, vcc, 0, v51, vcc
	v_add_co_u32_e32 v28, vcc, s36, v50
	v_and_b32_e32 v38, 0xffff0000, v38
	s_nop 0
	v_addc_co_u32_e32 v29, vcc, 0, v51, vcc
	v_add_co_u32_e32 v26, vcc, s50, v50
	v_lshlrev_b32_e32 v58, 16, v39
	s_nop 0
	v_addc_co_u32_e32 v27, vcc, 0, v51, vcc
	global_load_dwordx4 v[42:45], v[52:53], off nt
	global_load_dwordx4 v[22:25], v[36:37], off nt
	global_load_dwordx4 v[18:21], v[34:35], off nt
	global_load_dwordx4 v[14:17], v[32:33], off nt
	global_load_dwordx4 v[10:13], v[30:31], off nt
	global_load_dwordx4 v[6:9], v[28:29], off nt
	global_load_dwordx4 v[2:5], v[26:27], off nt
	s_waitcnt lgkmcnt(0)
	ds_read_b128 v[46:49], v0
	v_and_b32_e32 v39, 0xffff0000, v39
	v_lshlrev_b32_e32 v59, 16, v40
	v_and_b32_e32 v40, 0xffff0000, v40
	s_waitcnt lgkmcnt(0)
	v_lshlrev_b32_e32 v54, 16, v46
	v_and_b32_e32 v46, 0xffff0000, v46
	v_lshlrev_b32_e32 v55, 16, v47
	v_and_b32_e32 v47, 0xffff0000, v47
	v_mul_f32_e32 v46, v46, v38
	v_mul_f32_e32 v38, 0xbfb8aa3b, v38
	v_mul_f32_e32 v55, v55, v58
	v_mul_f32_e32 v58, 0xbfb8aa3b, v58
	v_mul_f32_e32 v47, v47, v39
	v_mul_f32_e32 v39, 0xbfb8aa3b, v39
	v_lshlrev_b32_e32 v56, 16, v48
	v_and_b32_e32 v48, 0xffff0000, v48
	v_mul_f32_e32 v54, v54, v57
	v_mul_f32_e32 v57, 0xbfb8aa3b, v57
	v_exp_f32_e32 v38, v38
	v_exp_f32_e32 v58, v58
	v_exp_f32_e32 v39, v39
	v_mul_f32_e32 v48, v48, v40
	v_mul_f32_e32 v40, 0xbfb8aa3b, v40
	v_exp_f32_e32 v57, v57
	v_exp_f32_e32 v40, v40
	v_add_f32_e32 v38, 1.0, v38
	v_add_f32_e32 v58, 1.0, v58
	v_add_f32_e32 v39, 1.0, v39
	v_add_f32_e32 v57, 1.0, v57
	v_rcp_f32_e32 v38, v38
	v_rcp_f32_e32 v58, v58
	v_rcp_f32_e32 v39, v39
	v_mul_f32_e32 v56, v56, v59
	v_mul_f32_e32 v59, 0xbfb8aa3b, v59
	v_add_f32_e32 v40, 1.0, v40
	v_rcp_f32_e32 v57, v57
	v_exp_f32_e32 v59, v59
	v_rcp_f32_e32 v40, v40
	v_mul_f32_e32 v38, v38, v46
	v_mul_f32_e32 v46, v58, v55
	v_mul_f32_e32 v39, v39, v47
	v_mul_f32_e32 v54, v57, v54
	v_cvt_pk_bf16_f32 v38, v54, v38
	v_cvt_pk_bf16_f32 v39, v46, v39
	v_lshlrev_b32_e32 v46, 16, v41
	v_add_f32_e32 v59, 1.0, v59
	v_mul_f32_e32 v40, v40, v48
	v_mul_f32_e32 v48, 0xbfb8aa3b, v46
	v_rcp_f32_e32 v59, v59
	v_exp_f32_e32 v48, v48
	v_and_b32_e32 v41, 0xffff0000, v41
	v_mul_f32_e32 v54, 0xbfb8aa3b, v41
	v_exp_f32_e32 v54, v54
	v_mul_f32_e32 v47, v59, v56
	v_add_f32_e32 v48, 1.0, v48
	v_cvt_pk_bf16_f32 v40, v47, v40
	v_lshlrev_b32_e32 v47, 16, v49
	v_rcp_f32_e32 v48, v48
	v_mul_f32_e32 v46, v47, v46
	v_add_f32_e32 v47, 1.0, v54
	v_rcp_f32_e32 v47, v47
	v_mul_f32_e32 v46, v48, v46
	v_and_b32_e32 v48, 0xffff0000, v49
	v_mul_f32_e32 v41, v48, v41
	v_mul_f32_e32 v41, v47, v41
	v_cvt_pk_bf16_f32 v41, v46, v41
	global_store_dwordx4 v[50:51], v[38:41], off
	ds_read_b128 v[46:49], v0 offset:1088
	s_waitcnt vmcnt(7)
	v_lshlrev_b32_e32 v38, 16, v42
	v_mul_f32_e32 v40, 0xbfb8aa3b, v38
	v_exp_f32_e32 v40, v40
	v_and_b32_e32 v41, 0xffff0000, v42
	v_mul_f32_e32 v42, 0xbfb8aa3b, v41
	v_exp_f32_e32 v42, v42
	v_add_f32_e32 v40, 1.0, v40
	s_waitcnt lgkmcnt(0)
; DI unsigned cvtpk(float lo, float hi) { unsigned r; asm volatile("v_cvt_pk_bf16_f32 %0, %1, %2" : "=v"(r) : "v"(lo), "v"(hi)); return r; }
; DI float bflo(unsigned w) { return __uint_as_float(w << 16); }
; DI float bfhi(unsigned w) { return __uint_as_float(w & 0xffff0000u); }
; DI float sigm(float x) { return rcpf_(1.f + ex2(-x * LOG2E)); }
; DI void attn_item(const bf16_t* __restrict__ Qw_, const bf16_t* __restrict__ Kh, const bf16_t* __restrict__ Vh, const bf16_t* Gw, bf16_t* Ow,
;                   int NT, int kt0, int qw, float sinkv, char* lds) {
;     ...
; #pragma unroll
;     for (int k = 0; k < 8; ++k) {
;         const u32x4 ov = *(const u32x4*)(OT + (er + 4 * k) * 136 + ec * 8); u32x4 w;
; #pragma unroll
;         for (int i = 0; i < 4; ++i) { const float g0 = bflo(gv[k][i]), g1 = bfhi(gv[k][i]); w[i] = cvtpk(bflo(ov[i]) * g0 * sigm(g0), bfhi(ov[i]) * g1 * sigm(g1)); }
;         __builtin_nontemporal_store(w, (u32x4*)(Ow + (size_t)(er + 4 * k) * 2048 + ec * 8));
;     }
	v_lshlrev_b32_e32 v39, 16, v46
	v_rcp_f32_e32 v40, v40
	v_mul_f32_e32 v38, v39, v38
	v_add_f32_e32 v39, 1.0, v42
	v_rcp_f32_e32 v39, v39
	v_mul_f32_e32 v38, v40, v38
	v_and_b32_e32 v40, 0xffff0000, v46
	v_mul_f32_e32 v40, v40, v41
	v_mul_f32_e32 v39, v39, v40
	v_cvt_pk_bf16_f32 v38, v38, v39
	v_lshlrev_b32_e32 v39, 16, v43
	v_mul_f32_e32 v41, 0xbfb8aa3b, v39
	v_exp_f32_e32 v41, v41
	v_and_b32_e32 v42, 0xffff0000, v43
	v_mul_f32_e32 v43, 0xbfb8aa3b, v42
	v_exp_f32_e32 v43, v43
	v_add_f32_e32 v41, 1.0, v41
	v_lshlrev_b32_e32 v40, 16, v47
	v_rcp_f32_e32 v41, v41
	v_mul_f32_e32 v39, v40, v39
	v_add_f32_e32 v40, 1.0, v43
	v_rcp_f32_e32 v40, v40
	v_mul_f32_e32 v39, v41, v39
	v_and_b32_e32 v41, 0xffff0000, v47
	v_mul_f32_e32 v41, v41, v42
	v_mul_f32_e32 v40, v40, v41
	v_cvt_pk_bf16_f32 v39, v39, v40
	v_lshlrev_b32_e32 v40, 16, v44
	v_mul_f32_e32 v42, 0xbfb8aa3b, v40
	v_exp_f32_e32 v42, v42
	v_and_b32_e32 v43, 0xffff0000, v44
	v_mul_f32_e32 v44, 0xbfb8aa3b, v43
	v_exp_f32_e32 v44, v44
	v_add_f32_e32 v42, 1.0, v42
	v_lshlrev_b32_e32 v41, 16, v48
	v_rcp_f32_e32 v42, v42
	v_mul_f32_e32 v40, v41, v40
	v_add_f32_e32 v41, 1.0, v44
	v_rcp_f32_e32 v41, v41
	v_mul_f32_e32 v40, v42, v40
	v_and_b32_e32 v42, 0xffff0000, v48
	v_mul_f32_e32 v42, v42, v43
	v_mul_f32_e32 v41, v41, v42
	v_cvt_pk_bf16_f32 v40, v40, v41
	v_lshlrev_b32_e32 v41, 16, v45
	v_mul_f32_e32 v43, 0xbfb8aa3b, v41
	v_exp_f32_e32 v43, v43
	v_and_b32_e32 v44, 0xffff0000, v45
	v_mul_f32_e32 v45, 0xbfb8aa3b, v44
	v_exp_f32_e32 v45, v45
	v_add_f32_e32 v43, 1.0, v43
	v_lshlrev_b32_e32 v42, 16, v49
	v_rcp_f32_e32 v43, v43
	v_mul_f32_e32 v41, v42, v41
	v_add_f32_e32 v42, 1.0, v45
	v_rcp_f32_e32 v42, v42
	v_mul_f32_e32 v41, v43, v41
	v_and_b32_e32 v43, 0xffff0000, v49
	v_mul_f32_e32 v43, v43, v44
	v_mul_f32_e32 v42, v42, v43
	v_cvt_pk_bf16_f32 v41, v41, v42
	global_store_dwordx4 v[52:53], v[38:41], off
	ds_read_b128 v[42:45], v0 offset:2176
	s_waitcnt vmcnt(7)
	v_lshlrev_b32_e32 v38, 16, v22
	v_mul_f32_e32 v40, 0xbfb8aa3b, v38
	v_exp_f32_e32 v40, v40
	v_and_b32_e32 v22, 0xffff0000, v22
	v_mul_f32_e32 v41, 0xbfb8aa3b, v22
	v_exp_f32_e32 v41, v41
	v_add_f32_e32 v40, 1.0, v40
	s_waitcnt lgkmcnt(0)
	v_lshlrev_b32_e32 v39, 16, v42
	v_rcp_f32_e32 v40, v40
	v_mul_f32_e32 v38, v39, v38
	v_add_f32_e32 v39, 1.0, v41
	v_rcp_f32_e32 v39, v39
	v_mul_f32_e32 v38, v40, v38
	v_and_b32_e32 v40, 0xffff0000, v42
	v_mul_f32_e32 v22, v40, v22
	v_mul_f32_e32 v22, v39, v22
	v_cvt_pk_bf16_f32 v22, v38, v22
	v_lshlrev_b32_e32 v38, 16, v23
	v_mul_f32_e32 v40, 0xbfb8aa3b, v38
	v_exp_f32_e32 v40, v40
	v_and_b32_e32 v23, 0xffff0000, v23
	v_mul_f32_e32 v41, 0xbfb8aa3b, v23
	v_exp_f32_e32 v41, v41
	v_add_f32_e32 v40, 1.0, v40
	v_lshlrev_b32_e32 v39, 16, v43
	v_rcp_f32_e32 v40, v40
	v_mul_f32_e32 v38, v39, v38
	v_add_f32_e32 v39, 1.0, v41
	v_rcp_f32_e32 v39, v39
	v_mul_f32_e32 v38, v40, v38
	v_and_b32_e32 v40, 0xffff0000, v43
	v_mul_f32_e32 v23, v40, v23
	v_mul_f32_e32 v23, v39, v23
	v_cvt_pk_bf16_f32 v23, v38, v23
	v_lshlrev_b32_e32 v38, 16, v24
	v_mul_f32_e32 v40, 0xbfb8aa3b, v38
	v_exp_f32_e32 v40, v40
	v_and_b32_e32 v24, 0xffff0000, v24
	v_mul_f32_e32 v41, 0xbfb8aa3b, v24
	v_exp_f32_e32 v41, v41
	v_add_f32_e32 v40, 1.0, v40
	v_lshlrev_b32_e32 v39, 16, v44
	v_rcp_f32_e32 v40, v40
	v_mul_f32_e32 v38, v39, v38
	v_add_f32_e32 v39, 1.0, v41
	v_rcp_f32_e32 v39, v39
	v_mul_f32_e32 v38, v40, v38
	v_and_b32_e32 v40, 0xffff0000, v44
	v_mul_f32_e32 v24, v40, v24
	v_mul_f32_e32 v24, v39, v24
	v_cvt_pk_bf16_f32 v24, v38, v24
	v_lshlrev_b32_e32 v38, 16, v25
	v_mul_f32_e32 v40, 0xbfb8aa3b, v38
	v_exp_f32_e32 v40, v40
	v_and_b32_e32 v25, 0xffff0000, v25
	v_mul_f32_e32 v41, 0xbfb8aa3b, v25
	v_exp_f32_e32 v41, v41
	v_add_f32_e32 v40, 1.0, v40
	v_lshlrev_b32_e32 v39, 16, v45
	v_rcp_f32_e32 v40, v40
	v_mul_f32_e32 v38, v39, v38
	v_add_f32_e32 v39, 1.0, v41
	v_rcp_f32_e32 v39, v39
	v_mul_f32_e32 v38, v40, v38
	v_and_b32_e32 v40, 0xffff0000, v45
	v_mul_f32_e32 v25, v40, v25
	v_mul_f32_e32 v25, v39, v25
	v_cvt_pk_bf16_f32 v25, v38, v25
	global_store_dwordx4 v[36:37], v[22:25], off
	ds_read_b128 v[38:41], v0 offset:3264
	s_waitcnt vmcnt(7)
	v_lshlrev_b32_e32 v22, 16, v18
	v_mul_f32_e32 v24, 0xbfb8aa3b, v22
	v_exp_f32_e32 v24, v24
	v_and_b32_e32 v18, 0xffff0000, v18
	v_mul_f32_e32 v25, 0xbfb8aa3b, v18
	v_exp_f32_e32 v25, v25
	v_add_f32_e32 v24, 1.0, v24
	s_waitcnt lgkmcnt(0)
	v_lshlrev_b32_e32 v23, 16, v38
	v_rcp_f32_e32 v24, v24
	v_mul_f32_e32 v22, v23, v22
	v_add_f32_e32 v23, 1.0, v25
	v_rcp_f32_e32 v23, v23
	v_mul_f32_e32 v22, v24, v22
	v_and_b32_e32 v24, 0xffff0000, v38
	v_mul_f32_e32 v18, v24, v18
	v_mul_f32_e32 v18, v23, v18
	v_cvt_pk_bf16_f32 v18, v22, v18
	v_lshlrev_b32_e32 v22, 16, v19
	v_mul_f32_e32 v24, 0xbfb8aa3b, v22
	v_exp_f32_e32 v24, v24
	v_and_b32_e32 v19, 0xffff0000, v19
	v_mul_f32_e32 v25, 0xbfb8aa3b, v19
	v_exp_f32_e32 v25, v25
	v_add_f32_e32 v24, 1.0, v24
	v_lshlrev_b32_e32 v23, 16, v39
	v_rcp_f32_e32 v24, v24
	v_mul_f32_e32 v22, v23, v22
	v_add_f32_e32 v23, 1.0, v25
	v_rcp_f32_e32 v23, v23
	v_mul_f32_e32 v22, v24, v22
	v_and_b32_e32 v24, 0xffff0000, v39
	v_mul_f32_e32 v19, v24, v19
	v_mul_f32_e32 v19, v23, v19
	v_cvt_pk_bf16_f32 v19, v22, v19
	v_lshlrev_b32_e32 v22, 16, v20
	v_mul_f32_e32 v24, 0xbfb8aa3b, v22
	v_exp_f32_e32 v24, v24
	v_and_b32_e32 v20, 0xffff0000, v20
	v_mul_f32_e32 v25, 0xbfb8aa3b, v20
	v_exp_f32_e32 v25, v25
	v_add_f32_e32 v24, 1.0, v24
	v_lshlrev_b32_e32 v23, 16, v40
	v_rcp_f32_e32 v24, v24
	v_mul_f32_e32 v22, v23, v22
	v_add_f32_e32 v23, 1.0, v25
	v_rcp_f32_e32 v23, v23
	v_mul_f32_e32 v22, v24, v22
	v_and_b32_e32 v24, 0xffff0000, v40
	v_mul_f32_e32 v20, v24, v20
	v_mul_f32_e32 v20, v23, v20
	v_cvt_pk_bf16_f32 v20, v22, v20
	v_lshlrev_b32_e32 v22, 16, v21
	v_mul_f32_e32 v24, 0xbfb8aa3b, v22
	v_exp_f32_e32 v24, v24
	v_and_b32_e32 v21, 0xffff0000, v21
	v_mul_f32_e32 v25, 0xbfb8aa3b, v21
	v_exp_f32_e32 v25, v25
	v_add_f32_e32 v24, 1.0, v24
	v_lshlrev_b32_e32 v23, 16, v41
	v_rcp_f32_e32 v24, v24
	v_mul_f32_e32 v22, v23, v22
	v_add_f32_e32 v23, 1.0, v25
	v_rcp_f32_e32 v23, v23
	v_mul_f32_e32 v22, v24, v22
	v_and_b32_e32 v24, 0xffff0000, v41
	v_mul_f32_e32 v21, v24, v21
	v_mul_f32_e32 v21, v23, v21
	v_cvt_pk_bf16_f32 v21, v22, v21
	global_store_dwordx4 v[34:35], v[18:21], off
	ds_read_b128 v[22:25], v0 offset:4352
	s_waitcnt vmcnt(7)
; DI unsigned cvtpk(float lo, float hi) { unsigned r; asm volatile("v_cvt_pk_bf16_f32 %0, %1, %2" : "=v"(r) : "v"(lo), "v"(hi)); return r; }
; DI float bflo(unsigned w) { return __uint_as_float(w << 16); }
; DI float bfhi(unsigned w) { return __uint_as_float(w & 0xffff0000u); }
; DI float sigm(float x) { return rcpf_(1.f + ex2(-x * LOG2E)); }
; DI void attn_item(const bf16_t* __restrict__ Qw_, const bf16_t* __restrict__ Kh, const bf16_t* __restrict__ Vh, const bf16_t* Gw, bf16_t* Ow,
;                   int NT, int kt0, int qw, float sinkv, char* lds) {
;     ...
; #pragma unroll
;     for (int k = 0; k < 8; ++k) {
;         const u32x4 ov = *(const u32x4*)(OT + (er + 4 * k) * 136 + ec * 8); u32x4 w;
; #pragma unroll
;         for (int i = 0; i < 4; ++i) { const float g0 = bflo(gv[k][i]), g1 = bfhi(gv[k][i]); w[i] = cvtpk(bflo(ov[i]) * g0 * sigm(g0), bfhi(ov[i]) * g1 * sigm(g1)); }
;         __builtin_nontemporal_store(w, (u32x4*)(Ow + (size_t)(er + 4 * k) * 2048 + ec * 8));
;     }
	v_lshlrev_b32_e32 v18, 16, v14
	v_mul_f32_e32 v20, 0xbfb8aa3b, v18
	v_exp_f32_e32 v20, v20
	v_and_b32_e32 v14, 0xffff0000, v14
	v_mul_f32_e32 v21, 0xbfb8aa3b, v14
	v_exp_f32_e32 v21, v21
	v_add_f32_e32 v20, 1.0, v20
	s_waitcnt lgkmcnt(0)
	v_lshlrev_b32_e32 v19, 16, v22
	v_rcp_f32_e32 v20, v20
	v_mul_f32_e32 v18, v19, v18
	v_add_f32_e32 v19, 1.0, v21
	v_rcp_f32_e32 v19, v19
	v_mul_f32_e32 v18, v20, v18
	v_and_b32_e32 v20, 0xffff0000, v22
	v_mul_f32_e32 v14, v20, v14
	v_mul_f32_e32 v14, v19, v14
	v_cvt_pk_bf16_f32 v14, v18, v14
	v_lshlrev_b32_e32 v18, 16, v15
	v_mul_f32_e32 v20, 0xbfb8aa3b, v18
	v_exp_f32_e32 v20, v20
	v_and_b32_e32 v15, 0xffff0000, v15
	v_mul_f32_e32 v21, 0xbfb8aa3b, v15
	v_exp_f32_e32 v21, v21
	v_add_f32_e32 v20, 1.0, v20
	v_lshlrev_b32_e32 v19, 16, v23
	v_rcp_f32_e32 v20, v20
	v_mul_f32_e32 v18, v19, v18
	v_add_f32_e32 v19, 1.0, v21
	v_rcp_f32_e32 v19, v19
	v_mul_f32_e32 v18, v20, v18
	v_and_b32_e32 v20, 0xffff0000, v23
	v_mul_f32_e32 v15, v20, v15
	v_mul_f32_e32 v15, v19, v15
	v_cvt_pk_bf16_f32 v15, v18, v15
	v_lshlrev_b32_e32 v18, 16, v16
	v_mul_f32_e32 v20, 0xbfb8aa3b, v18
	v_exp_f32_e32 v20, v20
	v_and_b32_e32 v16, 0xffff0000, v16
	v_mul_f32_e32 v21, 0xbfb8aa3b, v16
	v_exp_f32_e32 v21, v21
	v_add_f32_e32 v20, 1.0, v20
	v_lshlrev_b32_e32 v19, 16, v24
	v_rcp_f32_e32 v20, v20
	v_mul_f32_e32 v18, v19, v18
	v_add_f32_e32 v19, 1.0, v21
	v_rcp_f32_e32 v19, v19
	v_mul_f32_e32 v18, v20, v18
	v_and_b32_e32 v20, 0xffff0000, v24
	v_mul_f32_e32 v16, v20, v16
	v_mul_f32_e32 v16, v19, v16
	v_cvt_pk_bf16_f32 v16, v18, v16
	v_lshlrev_b32_e32 v18, 16, v17
	v_mul_f32_e32 v20, 0xbfb8aa3b, v18
	v_exp_f32_e32 v20, v20
	v_and_b32_e32 v17, 0xffff0000, v17
	v_mul_f32_e32 v21, 0xbfb8aa3b, v17
	v_exp_f32_e32 v21, v21
	v_add_f32_e32 v20, 1.0, v20
	v_lshlrev_b32_e32 v19, 16, v25
	v_rcp_f32_e32 v20, v20
	v_mul_f32_e32 v18, v19, v18
	v_add_f32_e32 v19, 1.0, v21
	v_rcp_f32_e32 v19, v19
	v_mul_f32_e32 v18, v20, v18
	v_and_b32_e32 v20, 0xffff0000, v25
	v_mul_f32_e32 v17, v20, v17
	v_mul_f32_e32 v17, v19, v17
	v_cvt_pk_bf16_f32 v17, v18, v17
	global_store_dwordx4 v[32:33], v[14:17], off
	ds_read_b128 v[18:21], v0 offset:5440
	s_waitcnt vmcnt(7)
	v_lshlrev_b32_e32 v14, 16, v10
	v_mul_f32_e32 v16, 0xbfb8aa3b, v14
	v_exp_f32_e32 v16, v16
	v_and_b32_e32 v10, 0xffff0000, v10
	v_mul_f32_e32 v17, 0xbfb8aa3b, v10
	v_exp_f32_e32 v17, v17
	v_add_f32_e32 v16, 1.0, v16
	s_waitcnt lgkmcnt(0)
	v_lshlrev_b32_e32 v15, 16, v18
	v_rcp_f32_e32 v16, v16
	v_mul_f32_e32 v14, v15, v14
	v_add_f32_e32 v15, 1.0, v17
	v_rcp_f32_e32 v15, v15
	v_mul_f32_e32 v14, v16, v14
	v_and_b32_e32 v16, 0xffff0000, v18
	v_mul_f32_e32 v10, v16, v10
	v_mul_f32_e32 v10, v15, v10
	v_cvt_pk_bf16_f32 v10, v14, v10
	v_lshlrev_b32_e32 v14, 16, v11
	v_mul_f32_e32 v16, 0xbfb8aa3b, v14
	v_exp_f32_e32 v16, v16
	v_and_b32_e32 v11, 0xffff0000, v11
	v_mul_f32_e32 v17, 0xbfb8aa3b, v11
	v_exp_f32_e32 v17, v17
	v_add_f32_e32 v16, 1.0, v16
	v_lshlrev_b32_e32 v15, 16, v19
	v_rcp_f32_e32 v16, v16
	v_mul_f32_e32 v14, v15, v14
	v_add_f32_e32 v15, 1.0, v17
	v_rcp_f32_e32 v15, v15
	v_mul_f32_e32 v14, v16, v14
	v_and_b32_e32 v16, 0xffff0000, v19
	v_mul_f32_e32 v11, v16, v11
	v_mul_f32_e32 v11, v15, v11
	v_cvt_pk_bf16_f32 v11, v14, v11
	v_lshlrev_b32_e32 v14, 16, v12
	v_mul_f32_e32 v16, 0xbfb8aa3b, v14
	v_exp_f32_e32 v16, v16
	v_and_b32_e32 v12, 0xffff0000, v12
	v_mul_f32_e32 v17, 0xbfb8aa3b, v12
	v_exp_f32_e32 v17, v17
	v_add_f32_e32 v16, 1.0, v16
	v_lshlrev_b32_e32 v15, 16, v20
	v_rcp_f32_e32 v16, v16
	v_mul_f32_e32 v14, v15, v14
	v_add_f32_e32 v15, 1.0, v17
	v_rcp_f32_e32 v15, v15
	v_mul_f32_e32 v14, v16, v14
	v_and_b32_e32 v16, 0xffff0000, v20
	v_mul_f32_e32 v12, v16, v12
	v_mul_f32_e32 v12, v15, v12
	v_cvt_pk_bf16_f32 v12, v14, v12
	v_lshlrev_b32_e32 v14, 16, v13
	v_mul_f32_e32 v16, 0xbfb8aa3b, v14
	v_exp_f32_e32 v16, v16
	v_and_b32_e32 v13, 0xffff0000, v13
	v_mul_f32_e32 v17, 0xbfb8aa3b, v13
	v_exp_f32_e32 v17, v17
	v_add_f32_e32 v16, 1.0, v16
	v_lshlrev_b32_e32 v15, 16, v21
	v_rcp_f32_e32 v16, v16
	v_mul_f32_e32 v14, v15, v14
	v_add_f32_e32 v15, 1.0, v17
	v_rcp_f32_e32 v15, v15
	v_mul_f32_e32 v14, v16, v14
	v_and_b32_e32 v16, 0xffff0000, v21
	v_mul_f32_e32 v13, v16, v13
	v_mul_f32_e32 v13, v15, v13
	v_cvt_pk_bf16_f32 v13, v14, v13
	global_store_dwordx4 v[30:31], v[10:13], off
	ds_read_b128 v[14:17], v0 offset:6528
	s_waitcnt vmcnt(7)
; DI unsigned cvtpk(float lo, float hi) { unsigned r; asm volatile("v_cvt_pk_bf16_f32 %0, %1, %2" : "=v"(r) : "v"(lo), "v"(hi)); return r; }
; DI float bflo(unsigned w) { return __uint_as_float(w << 16); }
; DI float bfhi(unsigned w) { return __uint_as_float(w & 0xffff0000u); }
; DI float sigm(float x) { return rcpf_(1.f + ex2(-x * LOG2E)); }
; DI void attn_item(const bf16_t* __restrict__ Qw_, const bf16_t* __restrict__ Kh, const bf16_t* __restrict__ Vh, const bf16_t* Gw, bf16_t* Ow,
;                   int NT, int kt0, int qw, float sinkv, char* lds) {
;     ...
; #pragma unroll
;     for (int k = 0; k < 8; ++k) {
;         const u32x4 ov = *(const u32x4*)(OT + (er + 4 * k) * 136 + ec * 8); u32x4 w;
; #pragma unroll
;         for (int i = 0; i < 4; ++i) { const float g0 = bflo(gv[k][i]), g1 = bfhi(gv[k][i]); w[i] = cvtpk(bflo(ov[i]) * g0 * sigm(g0), bfhi(ov[i]) * g1 * sigm(g1)); }
;         __builtin_nontemporal_store(w, (u32x4*)(Ow + (size_t)(er + 4 * k) * 2048 + ec * 8));
;     }
	v_lshlrev_b32_e32 v10, 16, v6
	v_mul_f32_e32 v12, 0xbfb8aa3b, v10
	v_exp_f32_e32 v12, v12
	v_and_b32_e32 v6, 0xffff0000, v6
	v_mul_f32_e32 v13, 0xbfb8aa3b, v6
	v_exp_f32_e32 v13, v13
	v_add_f32_e32 v12, 1.0, v12
	s_waitcnt lgkmcnt(0)
	v_lshlrev_b32_e32 v11, 16, v14
	v_rcp_f32_e32 v12, v12
	v_mul_f32_e32 v10, v11, v10
	v_add_f32_e32 v11, 1.0, v13
	v_rcp_f32_e32 v11, v11
	v_mul_f32_e32 v10, v12, v10
	v_and_b32_e32 v12, 0xffff0000, v14
	v_mul_f32_e32 v6, v12, v6
	v_mul_f32_e32 v6, v11, v6
	v_cvt_pk_bf16_f32 v6, v10, v6
	v_lshlrev_b32_e32 v10, 16, v7
	v_mul_f32_e32 v12, 0xbfb8aa3b, v10
	v_exp_f32_e32 v12, v12
	v_and_b32_e32 v7, 0xffff0000, v7
	v_mul_f32_e32 v13, 0xbfb8aa3b, v7
	v_exp_f32_e32 v13, v13
	v_add_f32_e32 v12, 1.0, v12
	v_lshlrev_b32_e32 v11, 16, v15
	v_rcp_f32_e32 v12, v12
	v_mul_f32_e32 v10, v11, v10
	v_add_f32_e32 v11, 1.0, v13
	v_rcp_f32_e32 v11, v11
	v_mul_f32_e32 v10, v12, v10
	v_and_b32_e32 v12, 0xffff0000, v15
	v_mul_f32_e32 v7, v12, v7
	v_mul_f32_e32 v7, v11, v7
	v_cvt_pk_bf16_f32 v7, v10, v7
	v_lshlrev_b32_e32 v10, 16, v8
	v_mul_f32_e32 v12, 0xbfb8aa3b, v10
	v_exp_f32_e32 v12, v12
	v_and_b32_e32 v8, 0xffff0000, v8
	v_mul_f32_e32 v13, 0xbfb8aa3b, v8
	v_exp_f32_e32 v13, v13
	v_add_f32_e32 v12, 1.0, v12
	v_lshlrev_b32_e32 v11, 16, v16
	v_rcp_f32_e32 v12, v12
	v_mul_f32_e32 v10, v11, v10
	v_add_f32_e32 v11, 1.0, v13
	v_rcp_f32_e32 v11, v11
	v_mul_f32_e32 v10, v12, v10
	v_and_b32_e32 v12, 0xffff0000, v16
	v_mul_f32_e32 v8, v12, v8
	v_mul_f32_e32 v8, v11, v8
	v_cvt_pk_bf16_f32 v8, v10, v8
	v_lshlrev_b32_e32 v10, 16, v9
	v_mul_f32_e32 v12, 0xbfb8aa3b, v10
	v_exp_f32_e32 v12, v12
	v_and_b32_e32 v9, 0xffff0000, v9
	v_mul_f32_e32 v13, 0xbfb8aa3b, v9
	v_exp_f32_e32 v13, v13
	v_add_f32_e32 v12, 1.0, v12
	v_lshlrev_b32_e32 v11, 16, v17
	v_rcp_f32_e32 v12, v12
	v_mul_f32_e32 v10, v11, v10
	v_add_f32_e32 v11, 1.0, v13
	v_rcp_f32_e32 v11, v11
	v_mul_f32_e32 v10, v12, v10
	v_and_b32_e32 v12, 0xffff0000, v17
	v_mul_f32_e32 v9, v12, v9
	v_mul_f32_e32 v9, v11, v9
	v_cvt_pk_bf16_f32 v9, v10, v9
	ds_read_b128 v[10:13], v0 offset:7616
	s_waitcnt vmcnt(6)
	v_lshlrev_b32_e32 v0, 16, v2
	global_store_dwordx4 v[28:29], v[6:9], off
	v_and_b32_e32 v2, 0xffff0000, v2
	s_nop 0
	v_mul_f32_e32 v7, 0xbfb8aa3b, v0
	v_exp_f32_e32 v7, v7
	v_mul_f32_e32 v8, 0xbfb8aa3b, v2
	v_exp_f32_e32 v8, v8
	s_waitcnt lgkmcnt(0)
	v_lshlrev_b32_e32 v6, 16, v10
	v_add_f32_e32 v7, 1.0, v7
	v_rcp_f32_e32 v7, v7
	v_mul_f32_e32 v0, v6, v0
	v_add_f32_e32 v6, 1.0, v8
	v_rcp_f32_e32 v6, v6
	v_mul_f32_e32 v0, v7, v0
	v_and_b32_e32 v7, 0xffff0000, v10
	v_mul_f32_e32 v2, v7, v2
	v_mul_f32_e32 v2, v6, v2
	v_cvt_pk_bf16_f32 v2, v0, v2
	v_lshlrev_b32_e32 v0, 16, v3
	v_mul_f32_e32 v7, 0xbfb8aa3b, v0
	v_exp_f32_e32 v7, v7
	v_and_b32_e32 v3, 0xffff0000, v3
	v_mul_f32_e32 v8, 0xbfb8aa3b, v3
	v_exp_f32_e32 v8, v8
	v_add_f32_e32 v7, 1.0, v7
	v_lshlrev_b32_e32 v6, 16, v11
	v_rcp_f32_e32 v7, v7
	v_mul_f32_e32 v0, v6, v0
	v_add_f32_e32 v6, 1.0, v8
	v_rcp_f32_e32 v6, v6
	v_mul_f32_e32 v0, v7, v0
	v_and_b32_e32 v7, 0xffff0000, v11
	v_mul_f32_e32 v3, v7, v3
	v_mul_f32_e32 v3, v6, v3
	v_cvt_pk_bf16_f32 v3, v0, v3
	v_lshlrev_b32_e32 v0, 16, v4
	v_mul_f32_e32 v7, 0xbfb8aa3b, v0
	v_exp_f32_e32 v7, v7
	v_and_b32_e32 v4, 0xffff0000, v4
	v_mul_f32_e32 v8, 0xbfb8aa3b, v4
	v_exp_f32_e32 v8, v8
	v_add_f32_e32 v7, 1.0, v7
	v_lshlrev_b32_e32 v6, 16, v12
	v_rcp_f32_e32 v7, v7
	v_mul_f32_e32 v0, v6, v0
	v_add_f32_e32 v6, 1.0, v8
	v_rcp_f32_e32 v6, v6
	v_mul_f32_e32 v0, v7, v0
	v_and_b32_e32 v7, 0xffff0000, v12
	v_mul_f32_e32 v4, v7, v4
	v_mul_f32_e32 v4, v6, v4
	v_cvt_pk_bf16_f32 v4, v0, v4
	v_lshlrev_b32_e32 v0, 16, v5
	v_mul_f32_e32 v7, 0xbfb8aa3b, v0
	v_exp_f32_e32 v7, v7
	v_and_b32_e32 v5, 0xffff0000, v5
	v_mul_f32_e32 v8, 0xbfb8aa3b, v5
	v_exp_f32_e32 v8, v8
	v_add_f32_e32 v7, 1.0, v7
	v_lshlrev_b32_e32 v6, 16, v13
	v_rcp_f32_e32 v7, v7
	v_mul_f32_e32 v0, v6, v0
	v_add_f32_e32 v6, 1.0, v8
	v_rcp_f32_e32 v6, v6
	v_mul_f32_e32 v0, v7, v0
	v_and_b32_e32 v7, 0xffff0000, v13
	v_mul_f32_e32 v5, v7, v5
	v_mul_f32_e32 v5, v6, v5
	v_cvt_pk_bf16_f32 v5, v0, v5
	global_store_dwordx4 v[26:27], v[2:5], off
	s_cbranch_scc0 .LBB0_265
